# SSD prompt scan: loop-invariant address arithmetic hoisted out of the chunk loop (persistent pointers, LDS addresses)
# speedup vs baseline: 1.0108x; 1.0108x over previous
.LBB0_706:
	s_or_b64 exec, exec, s[46:47]
	s_lshl_b64 s[44:45], s[44:45], 11
	s_lshl_b64 s[34:35], s[34:35], 1
	s_add_u32 s34, s50, s34
	s_addc_u32 s35, s90, s35
	s_lshl_b32 s41, s41, 5
	s_and_b32 s41, s41, 0x300
	s_waitcnt vmcnt(7)
	v_mul_f32_e32 v2, 0x3fb8aa3b, v4
	s_add_u32 s46, s34, s41
	v_lshlrev_b32_e32 v6, 6, v151
	s_mov_b32 s34, 0x8000
	v_exp_f32_e32 v163, v2
	v_and_b32_e32 v2, 0xfc00, v6
	v_bitop3_b32 v6, v6, s34, v145 bitop3:0x6c
	s_addc_u32 s47, s35, 0
	v_lshlrev_b32_e32 v2, 1, v2
	v_mov_b32_e32 v3, v50
	v_lshlrev_b32_e32 v4, 4, v151
	v_lshlrev_b32_e32 v6, 1, v6
	v_mov_b32_e32 v7, v50
	v_lshl_add_u64 v[2:3], s[46:47], 0, v[2:3]
	v_and_b32_e32 v4, 0xf0, v4
	v_mov_b32_e32 v5, v50
	v_lshl_add_u64 v[6:7], s[46:47], 0, v[6:7]
	v_and_b32_e32 v162, 63, v151
	v_lshl_add_u64 v[2:3], v[2:3], 0, v[4:5]
	v_lshl_add_u64 v[4:5], v[6:7], 0, v[4:5]
	v_ashrrev_i32_e32 v141, 31, v140
	global_load_dwordx4 v[102:105], v[2:3], off
	global_load_dwordx4 v[106:109], v[2:3], off offset:1024
	global_load_dwordx4 v[110:113], v[4:5], off
	global_load_dwordx4 v[114:117], v[4:5], off offset:1024
	v_or_b32_e32 v2, s44, v162
	v_mov_b32_e32 v3, s45
	v_lshl_add_u64 v[4:5], s[44:45], 0, v[140:141]
	v_lshlrev_b64 v[2:3], 7, v[2:3]
	v_lshlrev_b64 v[4:5], 11, v[4:5]
	s_and_b32 s34, s39, 0x3c0
	v_lshl_add_u64 v[2:3], s[20:21], 0, v[2:3]
	v_lshl_add_u64 v[4:5], s[52:53], 0, v[4:5]
	s_lshl_b32 s34, s34, 1
	s_mov_b32 s35, s11
	v_and_b32_e32 v165, 7, v151
	v_lshl_add_u64 v[2:3], v[2:3], 0, s[10:11]
	v_lshl_add_u64 v[4:5], v[4:5], 0, s[34:35]
	v_lshlrev_b32_e32 v6, 4, v165
	v_mov_b32_e32 v7, v50
	s_waitcnt lgkmcnt(0)
	s_barrier
	v_lshl_add_u64 v[4:5], v[4:5], 0, v[6:7]
	global_load_dword v18, v[2:3], off
	global_load_dwordx4 v[118:121], v[4:5], off nt
	s_add_u32 s48, s20, s10
	s_addc_u32 s49, s21, 0
	s_add_u32 s52, s52, s34
	s_addc_u32 s53, s53, 0
	s_add_u32 s54, s4, s10
	s_addc_u32 s55, s5, 0
	s_or_b32 s41, s44, 64
	s_lshl_b32 s34, s39, 1
	s_add_u32 s56, s0, s34
	v_lshlrev_b32_e32 v144, 3, v165
	s_mov_b32 s43, s45
	s_addc_u32 s57, s1, 0
	s_mov_b32 s66, 0
	s_mov_b64 s[70:71], 0
	s_mov_b32 s82, 0
	v_mov_b32_e32 v2, 0
	v_mov_b32_e32 v3, v166
	v_mov_b32_e32 v4, v166
	v_mov_b32_e32 v5, v166
	v_mov_b32_e32 v6, v166
	v_mov_b32_e32 v7, v166
	v_mov_b32_e32 v8, v166
	v_mov_b32_e32 v9, v166
	v_mov_b32_e32 v10, v166
	v_mov_b32_e32 v11, v166
	v_mov_b32_e32 v12, v166
	v_mov_b32_e32 v13, v166
	v_mov_b32_e32 v14, v166
	v_mov_b32_e32 v15, v166
	v_mov_b32_e32 v16, v166
	v_mov_b32_e32 v17, v166
	v_mov_b32_e32 v98, 0
	v_mov_b32_e32 v99, v166
	v_mov_b32_e32 v100, v166
	v_mov_b32_e32 v101, v166
	v_mov_b32_e32 v94, v166
	v_mov_b32_e32 v95, v166
	v_mov_b32_e32 v96, v166
	v_mov_b32_e32 v97, v166
	v_mov_b32_e32 v90, v166
	v_mov_b32_e32 v91, v166
	v_mov_b32_e32 v92, v166
	v_mov_b32_e32 v93, v166
	v_mov_b32_e32 v86, v166
	v_mov_b32_e32 v87, v166
	v_mov_b32_e32 v88, v166
	v_mov_b32_e32 v89, v166
	v_mov_b32_e32 v82, 0
	v_mov_b32_e32 v83, v166
	v_mov_b32_e32 v84, v166
	v_mov_b32_e32 v85, v166
	v_mov_b32_e32 v78, v166
	v_mov_b32_e32 v79, v166
	v_mov_b32_e32 v80, v166
	v_mov_b32_e32 v81, v166
	v_mov_b32_e32 v74, v166
	v_mov_b32_e32 v75, v166
	v_mov_b32_e32 v76, v166
	v_mov_b32_e32 v77, v166
	v_mov_b32_e32 v70, v166
	v_mov_b32_e32 v71, v166
	v_mov_b32_e32 v72, v166
	v_mov_b32_e32 v73, v166
	v_mov_b32_e32 v66, 0
	v_mov_b32_e32 v67, v166
	v_mov_b32_e32 v68, v166
	v_mov_b32_e32 v69, v166
	v_mov_b32_e32 v62, v166
	v_mov_b32_e32 v63, v166
	v_mov_b32_e32 v64, v166
	v_mov_b32_e32 v65, v166
	v_mov_b32_e32 v58, v166
	v_mov_b32_e32 v59, v166
	v_mov_b32_e32 v60, v166
	v_mov_b32_e32 v61, v166
	v_mov_b32_e32 v54, v166
	v_mov_b32_e32 v55, v166
	v_mov_b32_e32 v56, v166
	v_mov_b32_e32 v57, v166
	v_mov_b32_e32 v126, 0
	v_mov_b32_e32 v127, v166
	v_mov_b32_e32 v128, v166
	v_mov_b32_e32 v129, v166
	v_mov_b32_e32 v167, v151
	v_ashrrev_i32_e32 v146, 3, v151
	s_mov_b32 s98, 0x20000
	s_mov_b32 s99, 0
	v_lshlrev_b32_e32 v212, 4, v151
	v_lshrrev_b32_e32 v213, 2, v151
	v_and_b32_e32 v214, 15, v151
	v_bfe_u32 v215, v151, 6, 2
	v_and_b32_e32 v213, 12, v213
	v_bitop3_b32 v213, v213, v214, v215 bitop3:0x36
	v_and_b32_e32 v216, 0x3f00, v212
	v_lshlrev_b32_e32 v213, 4, v213
	v_add3_u32 v196, 0, v216, v213
	v_add_u32_e32 v217, 0x200, v151
	v_lshrrev_b32_e32 v218, 2, v217
	v_and_b32_e32 v218, 12, v218
	v_lshlrev_b32_e32 v219, 4, v217
	v_bitop3_b32 v218, v218, v214, v215 bitop3:0x36
	v_and_b32_e32 v219, 0x3f00, v219
	v_lshlrev_b32_e32 v218, 4, v218
	v_add3_u32 v197, 0, v219, v218
	v_lshlrev_b32_e32 v213, 3, v151
	v_and_b32_e32 v213, 0x78, v213
	v_lshl_add_u32 v216, v213, 1, 0
	v_bfe_u32 v218, v151, 4, 6
	v_mad_u32_u24 v198, v218, s58, v216
	v_lshrrev_b32_e32 v219, 4, v151
	v_bitop3_b32 v219, v219, 32, 63 bitop3:0x6c
	v_mad_u32_u24 v199, v219, s58, v216
	v_or_b32_e32 v204, 64, v218
	v_lshlrev_b32_e32 v204, 11, v204
	v_mov_b32_e32 v205, 0
	v_mov_b32_e32 v217, 0
	v_lshl_add_u64 v[204:205], s[46:47], 0, v[204:205]
	v_or_b32_e32 v206, 64, v219
	v_lshl_add_u64 v[204:205], v[204:205], 0, v[216:217]
	v_lshlrev_b32_e32 v206, 11, v206
	v_mov_b32_e32 v207, 0
	v_and_b32_e32 v200, -4, v146
	v_lshl_add_u64 v[206:207], s[46:47], 0, v[206:207]
	v_add_u32_e32 v202, 0x43, v200
	v_lshl_add_u64 v[206:207], v[206:207], 0, v[216:217]
	v_add_u32_e32 v200, 63, v200
	v_lshlrev_b32_e32 v202, 11, v202
	v_lshlrev_b32_e32 v200, 11, v200
	v_mov_b32_e32 v201, 0
	v_mov_b32_e32 v203, 0
	v_lshl_add_u64 v[200:201], v[142:143], 0, v[200:201]
	v_lshl_add_u64 v[202:203], v[142:143], 0, v[202:203]
	s_mov_b32 s100, 0x2000
	s_mov_b32 s101, 0
	s_mov_b32 s68, s41
	s_mov_b32 s69, s43
	v_mov_b32_e32 v208, v162
	v_mov_b32_e32 v209, 0
	v_mov_b32_e32 v210, v146
	v_mov_b32_e32 v211, 0
	v_lshl_add_u64 v[208:209], s[68:69], 0, v[208:209]
	v_lshl_add_u64 v[210:211], s[68:69], 0, v[210:211]
	v_lshlrev_b64 v[208:209], 7, v[208:209]
	v_lshlrev_b64 v[210:211], 11, v[210:211]
	v_lshl_add_u64 v[208:209], s[48:49], 0, v[208:209]
	v_lshl_add_u64 v[210:211], s[52:53], 0, v[210:211]
	v_and_b32_e32 v220, 0x70, v212
	v_mov_b32_e32 v221, 0
	v_mov_b32_e32 v213, 0
	v_lshl_add_u64 v[210:211], v[210:211], 0, v[220:221]
	v_mov_b32_e32 v212, v146
	v_and_b32_e32 v220, 7, v151
	v_lshl_add_u64 v[212:213], s[44:45], 0, v[212:213]
	v_lshlrev_b32_e32 v222, 4, v220
	v_lshlrev_b64 v[214:215], 7, v[212:213]
	v_lshlrev_b64 v[212:213], 12, v[212:213]
	v_mov_b32_e32 v223, 0
	v_lshl_add_u64 v[214:215], s[54:55], 0, v[214:215]
	v_lshl_add_u64 v[212:213], s[56:57], 0, v[212:213]
	v_lshrrev_b32_e32 v221, 3, v151
	v_lshl_add_u64 v[212:213], v[212:213], 0, v[222:223]
	v_lshlrev_b32_e32 v222, 1, v220
	v_lshlrev_b32_e32 v223, 8, v146
	v_bitop3_b32 v221, v222, v221, 15 bitop3:0x78
	v_add_u32_e32 v224, s63, v223
	v_lshlrev_b32_e32 v225, 5, v220
	v_lshl_add_u32 v216, v221, 4, v224
	s_mov_b32 vcc_lo, 0x1bc00
	v_bfe_u32 v226, v151, 3, 4
	v_add3_u32 v217, vcc_lo, v223, v225
	v_bitop3_b32 v226, v222, v226, 1 bitop3:0x36
	v_xor_b32_e32 v227, v146, v151
	v_lshl_add_u32 v218, v226, 4, v224
	v_lshlrev_b32_e32 v227, 4, v227
	v_lshl_add_u32 v228, v146, 7, s64
	v_and_b32_e32 v227, 0x70, v227
	s_movk_i32 vcc_lo, 0xf000
	v_lshlrev_b32_e32 v231, 1, v151
	v_add3_u32 v219, v228, v227, vcc_lo
	v_and_b32_e32 v231, 62, v231
	v_and_b32_e32 v232, -4, v146
	v_mul_u32_u24_e32 v231, 0x48, v231
	v_lshlrev_b32_e32 v232, 1, v232
	v_lshlrev_b32_e32 v231, 1, v231
	s_nop 0
	v_add3_u32 v229, 0, v231, v232
	v_add3_u32 v230, s60, v231, v232
	v_add_u32_e32 v229, 0xd000, v229
.LBB0_707:
	v_mov_b32_e32 v169, v153
	v_mov_b32_e32 v148, v162
	v_mov_b32_e32 v168, v150
	v_mov_b32_e32 v149, 0
	v_add_u32_e32 v19, s82, v148
	v_cmp_gt_i32_e32 vcc, s59, v19
	v_mov_b32_e32 v24, 0
	s_and_saveexec_b64 s[34:35], vcc
	s_cbranch_execz .LBB0_709
	s_waitcnt vmcnt(1)
	v_add_f32_e32 v18, v154, v18
	v_mul_f32_e64 v19, |v18|, s36
	v_exp_f32_e32 v19, v19
	v_max_f32_e32 v24, 0, v18
	v_add_f32_e32 v19, 1.0, v19
	v_log_f32_e32 v19, v19
	s_nop 0
	v_fmac_f32_e32 v24, 0x3f317218, v19
.LBB0_709:
	s_or_b64 exec, exec, s[34:35]
	s_add_i32 s67, s82, 64
	s_waitcnt vmcnt(1)
	v_add_u32_e32 v18, s67, v148
	v_cmp_gt_i32_e32 vcc, s59, v18
	s_and_saveexec_b64 s[34:35], vcc
	s_cbranch_execz .LBB0_711
	global_load_dword v149, v[208:209], off
	v_lshl_add_u64 v[208:209], v[208:209], 0, s[100:101]
.LBB0_711:
	s_or_b64 exec, exec, s[34:35]
	s_waitcnt lgkmcnt(2)
	v_add_u32_e32 v18, s67, v146
	v_cmp_gt_i32_e32 vcc, s59, v18
	s_and_saveexec_b64 s[34:35], vcc
	s_cbranch_execz .LBB0_713
	global_load_dwordx4 v[122:125], v[210:211], off nt
	v_lshl_add_u64 v[210:211], v[210:211], 0, s[98:99]

.LBB0_715:
	ds_write_b128 v196, v[102:105]
	ds_write_b128 v197, v[110:113]
	ds_write_b128 v198, v[106:109] offset:17408
	v_and_b32_e32 v51, 7, v167
	ds_write_b128 v199, v[114:117] offset:17408
	s_and_saveexec_b64 s[34:35], s[70:71]
	s_cbranch_execz .LBB0_718
	v_cmp_eq_u32_e32 vcc, 0, v51
	global_store_dwordx4 v[212:213], v[126:129], off
	v_lshl_add_u64 v[212:213], s[98:99], 1, v[212:213]
	s_and_b64 exec, exec, vcc
	s_cbranch_execz .LBB0_718
	global_store_dword v[214:215], v166, off
	v_lshl_add_u64 v[214:215], v[214:215], 0, s[100:101]
.LBB0_718:
	s_or_b64 exec, exec, s[34:35]
	v_sub_f32_e32 v18, s68, v25
	v_mul_f32_e32 v18, 0x3fb8aa3b, v18
	v_exp_f32_e32 v25, v18
	v_lshlrev_b32_e32 v18, 16, v156
	v_and_b32_e32 v19, 0xffff0000, v156
	v_lshlrev_b32_e32 v26, 16, v157
	v_and_b32_e32 v27, 0xffff0000, v157
	v_pk_fma_f32 v[18:19], v[132:133], v[18:19], v[138:139]
	v_mul_f32_e32 v43, v24, v25
	v_lshlrev_b32_e32 v24, 16, v159
	v_and_b32_e32 v25, 0xffff0000, v159
	v_pk_fma_f32 v[18:19], v[134:135], v[26:27], v[18:19]
	v_lshlrev_b32_e32 v28, 16, v158
	v_and_b32_e32 v29, 0xffff0000, v158
	v_pk_fma_f32 v[18:19], v[136:137], v[24:25], v[18:19]
	s_lshl_b32 s34, s33, 3
	v_pk_fma_f32 v[18:19], v[130:131], v[28:29], v[18:19]
	s_or_b32 s68, s34, 4
	v_pk_mul_f32 v[36:37], v[18:19], s[36:37] op_sel_hi:[1,0]
	v_pk_fma_f32 v[26:27], v[132:133], v[26:27], v[138:139]
	v_exp_f32_e32 v36, v36
	v_exp_f32_e32 v37, v37
	v_readlane_b32 s35, v43, s34
	v_readlane_b32 s68, v43, s68
	v_pk_fma_f32 v[26:27], v[134:135], v[24:25], v[26:27]
	v_pk_add_f32 v[36:37], v[36:37], 1.0 op_sel_hi:[1,0]
	v_lshlrev_b32_e32 v30, 16, v160
	v_rcp_f32_e32 v36, v36
	v_rcp_f32_e32 v37, v37
	v_and_b32_e32 v31, 0xffff0000, v160
	v_mov_b32_e32 v38, s68
	v_mov_b32_e32 v39, s35
	v_cmp_eq_u32_e32 vcc, 0, v169
	v_pk_fma_f32 v[26:27], v[136:137], v[28:29], v[26:27]
	v_pk_mul_f32 v[18:19], v[18:19], v[36:37]
	v_cndmask_b32_e32 v38, v38, v39, vcc
	v_pk_fma_f32 v[26:27], v[130:131], v[30:31], v[26:27]
	v_pk_mul_f32 v[36:37], v[18:19], v[38:39] op_sel_hi:[1,0]
	v_pk_mul_f32 v[38:39], v[26:27], s[36:37] op_sel_hi:[1,0]
	v_pk_fma_f32 v[24:25], v[132:133], v[24:25], v[138:139]
	v_exp_f32_e32 v38, v38
	v_exp_f32_e32 v39, v39
	v_pk_fma_f32 v[24:25], v[134:135], v[28:29], v[24:25]
	v_pk_fma_f32 v[28:29], v[132:133], v[28:29], v[138:139]
	v_lshlrev_b32_e32 v32, 16, v161
	v_and_b32_e32 v33, 0xffff0000, v161
	v_pk_add_f32 v[38:39], v[38:39], 1.0 op_sel_hi:[1,0]
	v_pk_fma_f32 v[28:29], v[134:135], v[30:31], v[28:29]
	v_lshlrev_b32_e32 v34, 16, v164
	v_and_b32_e32 v35, 0xffff0000, v164
	v_rcp_f32_e32 v38, v38
	v_rcp_f32_e32 v39, v39
	v_pk_fma_f32 v[28:29], v[136:137], v[32:33], v[28:29]
	s_or_b32 s35, s34, 1
	s_or_b32 s68, s34, 5
	v_pk_fma_f32 v[28:29], v[130:131], v[34:35], v[28:29]
	v_readlane_b32 s35, v43, s35
	v_readlane_b32 s68, v43, s68
	v_pk_fma_f32 v[24:25], v[136:137], v[30:31], v[24:25]
	v_pk_mul_f32 v[30:31], v[28:29], s[36:37] op_sel_hi:[1,0]
	v_mov_b32_e32 v40, s68
	v_mov_b32_e32 v41, s35
	v_exp_f32_e32 v30, v30
	v_exp_f32_e32 v31, v31
	v_cndmask_b32_e32 v40, v40, v41, vcc
	v_pk_mul_f32 v[26:27], v[26:27], v[38:39]
	v_pk_fma_f32 v[24:25], v[130:131], v[32:33], v[24:25]
	v_pk_mul_f32 v[38:39], v[26:27], v[40:41] op_sel_hi:[1,0]
	v_pk_mul_f32 v[40:41], v[24:25], s[36:37] op_sel_hi:[1,0]
	s_or_b32 s35, s34, 2
	v_exp_f32_e32 v40, v40
	v_exp_f32_e32 v41, v41
	v_pk_add_f32 v[30:31], v[30:31], 1.0 op_sel_hi:[1,0]
	v_readlane_b32 s35, v43, s35
	v_rcp_f32_e32 v30, v30
	v_rcp_f32_e32 v31, v31
	s_or_b32 s68, s34, 6
	v_mov_b32_e32 v44, s35
	s_or_b32 s35, s34, 3
	s_or_b32 s34, s34, 7
	v_pk_add_f32 v[40:41], v[40:41], 1.0 op_sel_hi:[1,0]
	v_readlane_b32 s35, v43, s35
	v_readlane_b32 s34, v43, s34
	v_rcp_f32_e32 v40, v40
	v_rcp_f32_e32 v41, v41
	v_mov_b32_e32 v32, s34
	v_mov_b32_e32 v33, s35
	v_cndmask_b32_e32 v32, v32, v33, vcc
	v_pk_mul_f32 v[28:29], v[28:29], v[30:31]
	v_readlane_b32 s68, v43, s68
	v_pk_mul_f32 v[30:31], v[28:29], v[32:33] op_sel_hi:[1,0]
	v_cvt_pk_bf16_f32 v32, v18, v26
	v_mov_b32_e32 v42, s68
	v_cndmask_b32_e32 v42, v42, v44, vcc
	v_pk_mul_f32 v[24:25], v[24:25], v[40:41]
	v_pk_mul_f32 v[40:41], v[24:25], v[42:43] op_sel_hi:[1,0]
	v_cvt_pk_bf16_f32 v33, v24, v28
	v_cvt_pk_bf16_f32 v24, v19, v27
	v_cvt_pk_bf16_f32 v27, v40, v30
	s_cmpk_gt_u32 s82, 0x7bf
	v_cvt_pk_bf16_f32 v25, v25, v29
	v_cvt_pk_bf16_f32 v29, v41, v31
	s_cselect_b64 s[68:69], -1, 0
	v_cvt_pk_bf16_f32 v26, v36, v38
	v_cvt_pk_bf16_f32 v28, v37, v39
	s_and_b64 vcc, exec, s[68:69]
	ds_write2_b64 v229, v[32:33], v[24:25] offset1:18
	ds_write2_b64 v230, v[26:27], v[28:29] offset1:18
	s_cbranch_vccnz .LBB0_720
	global_load_dword v156, v[200:201], off offset:-4096
	global_load_dword v157, v[200:201], off offset:-2048
	global_load_dword v159, v[200:201], off
	global_load_dword v158, v[200:201], off offset:2048
	global_load_dword v160, v[202:203], off offset:-4096
	global_load_dword v161, v[202:203], off offset:-2048
	global_load_dword v164, v[202:203], off
	global_load_dwordx4 v[102:105], v[204:205], off
	global_load_dwordx4 v[106:109], v[204:205], off offset:1024
	global_load_dwordx4 v[110:113], v[206:207], off
	global_load_dwordx4 v[114:117], v[206:207], off offset:1024
	v_lshl_add_u64 v[200:201], v[200:201], 0, s[98:99]
	v_lshl_add_u64 v[202:203], v[202:203], 0, s[98:99]
	v_lshl_add_u64 v[204:205], v[204:205], 0, s[98:99]
	v_lshl_add_u64 v[206:207], v[206:207], 0, s[98:99]

.LBB0_738:
	s_waitcnt lgkmcnt(0)
	s_barrier
	s_waitcnt lgkmcnt(0)
	s_barrier
	v_add_u32_e32 v34, s82, v146
	v_cmp_gt_i32_e64 s[70:71], s59, v34
	s_and_saveexec_b64 s[82:83], s[70:71]
	s_cbranch_execz .LBB0_742
	ds_read_b128 v[34:37], v216
	ds_read_b128 v[38:41], v217
	ds_read_b128 v[42:45], v217 offset:16
	v_cmp_lt_i32_e32 vcc, 31, v146
	s_waitcnt lgkmcnt(1)
	v_pk_add_f32 v[36:37], v[36:37], v[40:41]
	v_pk_add_f32 v[40:41], v[34:35], v[38:39]
	ds_read_b128 v[46:49], v218
	s_waitcnt lgkmcnt(0)
	v_pk_add_f32 v[34:35], v[48:49], v[44:45]
	v_pk_add_f32 v[38:39], v[46:47], v[42:43]
	s_and_saveexec_b64 s[34:35], vcc
	s_cbranch_execz .LBB0_741
	ds_read_b128 v[42:45], v219
	s_waitcnt lgkmcnt(0)
	v_lshlrev_b32_e32 v46, 16, v42
	v_and_b32_e32 v47, 0xffff0000, v42
	v_lshlrev_b32_e32 v42, 16, v43
	v_and_b32_e32 v43, 0xffff0000, v43
	v_pk_add_f32 v[36:37], v[36:37], v[42:43]
	v_lshlrev_b32_e32 v42, 16, v44
	v_and_b32_e32 v43, 0xffff0000, v44
	v_lshlrev_b32_e32 v44, 16, v45
	v_and_b32_e32 v45, 0xffff0000, v45
	v_pk_add_f32 v[40:41], v[40:41], v[46:47]
	v_pk_add_f32 v[34:35], v[34:35], v[44:45]
	v_pk_add_f32 v[38:39], v[38:39], v[42:43]

	.amdhsa_kernel _Z8skel_fwd4Args
		.amdhsa_group_segment_fixed_size 0
		.amdhsa_private_segment_fixed_size 0
		.amdhsa_kernarg_size 536
		.amdhsa_user_sgpr_count 2
		.amdhsa_user_sgpr_dispatch_ptr 0
		.amdhsa_user_sgpr_queue_ptr 0
		.amdhsa_user_sgpr_kernarg_segment_ptr 1
		.amdhsa_user_sgpr_dispatch_id 0
		.amdhsa_user_sgpr_kernarg_preload_length 0
		.amdhsa_user_sgpr_kernarg_preload_offset 0
		.amdhsa_user_sgpr_private_segment_size 0
		.amdhsa_uses_dynamic_stack 0
		.amdhsa_enable_private_segment 0
		.amdhsa_system_sgpr_workgroup_id_x 1
		.amdhsa_system_sgpr_workgroup_id_y 0
		.amdhsa_system_sgpr_workgroup_id_z 0
		.amdhsa_system_sgpr_workgroup_info 0
		.amdhsa_system_vgpr_workitem_id 0
		.amdhsa_next_free_vgpr 256
		.amdhsa_next_free_sgpr 102
		.amdhsa_accum_offset 256
		.amdhsa_reserve_vcc 1
		.amdhsa_float_round_mode_32 0
		.amdhsa_float_round_mode_16_64 0
		.amdhsa_float_denorm_mode_32 3
		.amdhsa_float_denorm_mode_16_64 3
		.amdhsa_dx10_clamp 1
		.amdhsa_ieee_mode 1
		.amdhsa_fp16_overflow 0
		.amdhsa_tg_split 0
		.amdhsa_exception_fp_ieee_invalid_op 0
		.amdhsa_exception_fp_denorm_src 0
		.amdhsa_exception_fp_ieee_div_zero 0
		.amdhsa_exception_fp_ieee_overflow 0
		.amdhsa_exception_fp_ieee_underflow 0
		.amdhsa_exception_fp_ieee_inexact 0
		.amdhsa_exception_int_div_zero 0
	.end_amdhsa_kernel

amdhsa.kernels:
  - .agpr_count:     0
    .args:
      - .offset:         0
        .size:           280
        .value_kind:     by_value
      - .offset:         280
        .size:           4
        .value_kind:     hidden_block_count_x
      - .offset:         284
        .size:           4
        .value_kind:     hidden_block_count_y
      - .offset:         288
        .size:           4
        .value_kind:     hidden_block_count_z
      - .offset:         292
        .size:           2
        .value_kind:     hidden_group_size_x
      - .offset:         294
        .size:           2
        .value_kind:     hidden_group_size_y
      - .offset:         296
        .size:           2
        .value_kind:     hidden_group_size_z
      - .offset:         298
        .size:           2
        .value_kind:     hidden_remainder_x
      - .offset:         300
        .size:           2
        .value_kind:     hidden_remainder_y
      - .offset:         302
        .size:           2
        .value_kind:     hidden_remainder_z
      - .offset:         320
        .size:           8
        .value_kind:     hidden_global_offset_x
      - .offset:         328
        .size:           8
        .value_kind:     hidden_global_offset_y
      - .offset:         336
        .size:           8
        .value_kind:     hidden_global_offset_z
      - .offset:         344
        .size:           2
        .value_kind:     hidden_grid_dims
      - .offset:         400
        .size:           4
        .value_kind:     hidden_dynamic_lds_size
    .group_segment_fixed_size: 0
    .kernarg_segment_align: 8
    .kernarg_segment_size: 536
    .language:       OpenCL C
    .language_version:
      - 2
      - 0
    .max_flat_workgroup_size: 512
    .name:           _Z8skel_fwd4Args
    .private_segment_fixed_size: 0
    .sgpr_count:     108
    .sgpr_spill_count: 56
    .symbol:         _Z8skel_fwd4Args.kd
    .uniform_work_group_size: 1
    .uses_dynamic_stack: false
    .vgpr_count:     256
    .vgpr_spill_count: 0
    .wavefront_size: 64
